# attention: waves 4-7 raise issue priority during their start-of-trip softmax (the longest segment of a trip), back to 0 at the PV block
# speedup vs baseline: 1.0137x; 1.0067x over previous
.LBB0_252:
	s_cmp_lg_u32 s53, 0
	s_cselect_b64 s[14:15], -1, 0
	s_and_b64 s[36:37], s[4:5], s[14:15]
	s_andn2_b64 vcc, exec, s[36:37]
	s_cbranch_vccnz .LBB0_277
	s_setprio 2
	s_andn2_b64 vcc, exec, s[8:9]
	s_mov_b64 s[18:19], 0
	s_cbranch_vccnz .LBB0_282
	v_cndmask_b32_e64 v0, 0, 1, s[30:31]
	v_cmp_ne_u32_e64 s[38:39], 1, v0
	s_andn2_b64 vcc, exec, s[30:31]
	s_mov_b64 s[16:17], -1
	s_cbranch_vccnz .LBB0_256
	v_add_u32_e32 v0, 0, v189
	v_add_u32_e32 v12, 0x19f0c, v0
	v_add_u32_e32 v13, 0x19f14, v0
	v_add_u32_e32 v2, 0x19f3c, v0
	v_add_u32_e32 v3, 0x19f44, v0
	v_add_u32_e32 v4, 0x19f4c, v0
	v_add_u32_e32 v10, 0x19efc, v0
	v_add_u32_e32 v11, 0x19f04, v0
	v_add_u32_e32 v0, 0x19f54, v0
	ds_read2_b32 v[6:7], v2 offset1:1
	ds_read2_b32 v[8:9], v3 offset1:1
	ds_read2_b32 v[2:3], v4 offset1:1
	ds_read2_b32 v[4:5], v0 offset1:1
	ds_read2_b32 v[152:153], v10 offset1:1
	ds_read2_b32 v[14:15], v11 offset1:1
	ds_read2_b32 v[154:155], v12 offset1:1
	ds_read2_b32 v[12:13], v13 offset1:1
	s_waitcnt lgkmcnt(0)
	v_pk_fma_f32 v[4:5], v[110:111], s[0:1], v[4:5] op_sel_hi:[1,0,1]
	v_pk_fma_f32 v[2:3], v[108:109], s[0:1], v[2:3] op_sel_hi:[1,0,1]
	v_pk_fma_f32 v[10:11], v[106:107], s[0:1], v[8:9] op_sel_hi:[1,0,1]
	v_pk_fma_f32 v[6:7], v[104:105], s[0:1], v[6:7] op_sel_hi:[1,0,1]
	v_pk_fma_f32 v[12:13], v[102:103], s[0:1], v[12:13] op_sel_hi:[1,0,1]
	v_pk_fma_f32 v[8:9], v[100:101], s[0:1], v[154:155] op_sel_hi:[1,0,1]
	v_pk_fma_f32 v[14:15], v[98:99], s[0:1], v[14:15] op_sel_hi:[1,0,1]
	v_pk_fma_f32 v[152:153], v[96:97], s[0:1], v[152:153] op_sel_hi:[1,0,1]
	s_mov_b64 s[16:17], 0

; __device__ __forceinline__ void attn_unit(LAS unsigned char* lds, int b, int hh, int qb, const bf16_t* QK, const bf16_t* VT, bf16_t* CAT) {
;     ...
;         if (!lead && t >= 1) ATT_SOFTMAX(t - 1);
;         if (t >= 1) ATT_PV(t - 1);
.LBB0_277:
	s_setprio 0
	s_andn2_b64 vcc, exec, s[14:15]
	s_cbranch_vccnz .LBB0_283

.LBB0_324:
	s_cmp_lg_u32 s67, 0
	s_cselect_b64 s[14:15], -1, 0
	s_and_b64 s[36:37], s[4:5], s[14:15]
	s_andn2_b64 vcc, exec, s[36:37]
	s_cbranch_vccnz .LBB0_349
	s_setprio 2
	s_andn2_b64 vcc, exec, s[8:9]
	s_mov_b64 s[18:19], 0
	s_cbranch_vccnz .LBB0_354
	v_cndmask_b32_e64 v0, 0, 1, s[30:31]
	v_cmp_ne_u32_e64 s[38:39], 1, v0
	s_andn2_b64 vcc, exec, s[30:31]
	s_mov_b64 s[16:17], -1
	s_cbranch_vccnz .LBB0_328
	v_add_u32_e32 v0, 0, v190
	v_add_u32_e32 v12, 0x1870c, v0
	v_add_u32_e32 v13, 0x18714, v0
	v_add_u32_e32 v2, 0x1873c, v0
	v_add_u32_e32 v3, 0x18744, v0
	v_add_u32_e32 v4, 0x1874c, v0
	v_add_u32_e32 v10, 0x186fc, v0
	v_add_u32_e32 v11, 0x18704, v0
	v_add_u32_e32 v0, 0x18754, v0
	ds_read2_b32 v[6:7], v2 offset1:1
	ds_read2_b32 v[8:9], v3 offset1:1
	ds_read2_b32 v[2:3], v4 offset1:1
	ds_read2_b32 v[4:5], v0 offset1:1
	ds_read2_b32 v[14:15], v10 offset1:1
	ds_read2_b32 v[152:153], v11 offset1:1
	ds_read2_b32 v[154:155], v12 offset1:1
	ds_read2_b32 v[12:13], v13 offset1:1
	s_waitcnt lgkmcnt(0)
	v_pk_fma_f32 v[4:5], v[110:111], s[0:1], v[4:5] op_sel_hi:[1,0,1]
	v_pk_fma_f32 v[2:3], v[108:109], s[0:1], v[2:3] op_sel_hi:[1,0,1]
	v_pk_fma_f32 v[10:11], v[106:107], s[0:1], v[8:9] op_sel_hi:[1,0,1]
	v_pk_fma_f32 v[6:7], v[104:105], s[0:1], v[6:7] op_sel_hi:[1,0,1]
	v_pk_fma_f32 v[12:13], v[102:103], s[0:1], v[12:13] op_sel_hi:[1,0,1]
	v_pk_fma_f32 v[8:9], v[100:101], s[0:1], v[154:155] op_sel_hi:[1,0,1]
	v_pk_fma_f32 v[152:153], v[98:99], s[0:1], v[152:153] op_sel_hi:[1,0,1]
	v_pk_fma_f32 v[14:15], v[96:97], s[0:1], v[14:15] op_sel_hi:[1,0,1]
	s_mov_b64 s[16:17], 0

; __device__ __forceinline__ void attn_unit(LAS unsigned char* lds, int b, int hh, int qb, const bf16_t* QK, const bf16_t* VT, bf16_t* CAT) {
;     ...
;         if (!lead && t >= 1) ATT_SOFTMAX(t - 1);
.LBB0_399:
	s_cmp_lg_u32 s1, 0
	s_cselect_b64 s[14:15], -1, 0
	s_and_b64 s[36:37], s[4:5], s[14:15]
	s_andn2_b64 vcc, exec, s[36:37]
	s_cbranch_vccnz .LBB0_424
	s_setprio 2
	s_andn2_b64 vcc, exec, s[8:9]
	s_mov_b64 s[18:19], 0
	s_cbranch_vccnz .LBB0_429
	v_cndmask_b32_e64 v0, 0, 1, s[30:31]
	v_cmp_ne_u32_e64 s[38:39], 1, v0
	s_andn2_b64 vcc, exec, s[30:31]
	s_mov_b64 s[16:17], -1
	s_cbranch_vccnz .LBB0_403
	v_add_u32_e32 v0, 0, v190
	v_add_u32_e32 v12, 0x19b0c, v0
	v_add_u32_e32 v13, 0x19b14, v0
	v_add_u32_e32 v2, 0x19b3c, v0
	v_add_u32_e32 v3, 0x19b44, v0
	v_add_u32_e32 v4, 0x19b4c, v0
	v_add_u32_e32 v10, 0x19afc, v0
	v_add_u32_e32 v11, 0x19b04, v0
	v_add_u32_e32 v0, 0x19b54, v0
	ds_read2_b32 v[6:7], v2 offset1:1
	ds_read2_b32 v[8:9], v3 offset1:1
	ds_read2_b32 v[2:3], v4 offset1:1
	ds_read2_b32 v[4:5], v0 offset1:1
	ds_read2_b32 v[14:15], v10 offset1:1
	ds_read2_b32 v[152:153], v11 offset1:1
	ds_read2_b32 v[154:155], v12 offset1:1
	ds_read2_b32 v[12:13], v13 offset1:1
	s_waitcnt lgkmcnt(0)
	v_pk_fma_f32 v[4:5], v[110:111], s[0:1], v[4:5] op_sel_hi:[1,0,1]
	v_pk_fma_f32 v[2:3], v[108:109], s[0:1], v[2:3] op_sel_hi:[1,0,1]
	v_pk_fma_f32 v[10:11], v[106:107], s[0:1], v[8:9] op_sel_hi:[1,0,1]
	v_pk_fma_f32 v[6:7], v[104:105], s[0:1], v[6:7] op_sel_hi:[1,0,1]
	v_pk_fma_f32 v[12:13], v[102:103], s[0:1], v[12:13] op_sel_hi:[1,0,1]
	v_pk_fma_f32 v[8:9], v[100:101], s[0:1], v[154:155] op_sel_hi:[1,0,1]
	v_pk_fma_f32 v[152:153], v[98:99], s[0:1], v[152:153] op_sel_hi:[1,0,1]
	v_pk_fma_f32 v[14:15], v[96:97], s[0:1], v[14:15] op_sel_hi:[1,0,1]
	s_mov_b64 s[16:17], 0

; __device__ __forceinline__ void attn_unit(LAS unsigned char* lds, int b, int hh, int qb, const bf16_t* QK, const bf16_t* VT, bf16_t* CAT) {
;     ...
;         if (!lead && t >= 1) ATT_SOFTMAX(t - 1);
.LBB0_472:
	s_cmp_lg_u32 s48, 0
	s_cselect_b64 s[14:15], -1, 0
	s_and_b64 s[36:37], s[4:5], s[14:15]
	s_andn2_b64 vcc, exec, s[36:37]
	s_cbranch_vccnz .LBB0_497
	s_setprio 2
	s_andn2_b64 vcc, exec, s[8:9]
	s_mov_b64 s[18:19], 0
	s_cbranch_vccnz .LBB0_502
	v_cndmask_b32_e64 v138, 0, 1, s[30:31]
	v_cmp_ne_u32_e64 s[38:39], 1, v138
	s_andn2_b64 vcc, exec, s[30:31]
	s_mov_b64 s[16:17], -1
	s_cbranch_vccnz .LBB0_476
	v_add_u32_e32 v138, 0, v183
	v_add_u32_e32 v154, 0x19f0c, v138
	v_add_u32_e32 v155, 0x19f14, v138
	v_add_u32_e32 v139, 0x19f3c, v138
	v_add_u32_e32 v140, 0x19f44, v138
	v_add_u32_e32 v141, 0x19f4c, v138
	v_add_u32_e32 v156, 0x19f54, v138
	v_add_u32_e32 v152, 0x19efc, v138
	v_add_u32_e32 v153, 0x19f04, v138
	ds_read2_b32 v[142:143], v139 offset1:1
	ds_read2_b32 v[144:145], v140 offset1:1
	ds_read2_b32 v[138:139], v141 offset1:1
	ds_read2_b32 v[140:141], v156 offset1:1
	ds_read2_b32 v[156:157], v152 offset1:1
	ds_read2_b32 v[158:159], v153 offset1:1
	ds_read2_b32 v[190:191], v154 offset1:1
	ds_read2_b32 v[154:155], v155 offset1:1
	s_waitcnt lgkmcnt(0)
	v_pk_fma_f32 v[140:141], v[96:97], s[0:1], v[140:141] op_sel_hi:[1,0,1]
	v_pk_fma_f32 v[138:139], v[94:95], s[0:1], v[138:139] op_sel_hi:[1,0,1]
	v_pk_fma_f32 v[152:153], v[92:93], s[0:1], v[144:145] op_sel_hi:[1,0,1]
	v_pk_fma_f32 v[142:143], v[90:91], s[0:1], v[142:143] op_sel_hi:[1,0,1]
	v_pk_fma_f32 v[154:155], v[88:89], s[0:1], v[154:155] op_sel_hi:[1,0,1]
	v_pk_fma_f32 v[144:145], v[86:87], s[0:1], v[190:191] op_sel_hi:[1,0,1]
	v_pk_fma_f32 v[158:159], v[84:85], s[0:1], v[158:159] op_sel_hi:[1,0,1]
	v_pk_fma_f32 v[156:157], v[82:83], s[0:1], v[156:157] op_sel_hi:[1,0,1]
	s_mov_b64 s[16:17], 0
